# r3 gate-row loads issued one stage earlier; attention pass prologue no longer drains the Q-row loads before issuing the first K/V tile DMAs
# baseline (speedup 1.0000x reference)
; #define LAS __attribute__((address_space(3)))
; __device__ __forceinline__ int seqidx(int b, int hl, int dir, int c) { return ((b * 8 + hl) * 2 + dir) * 64 + c; }
; __device__ __forceinline__ u32x4 pack8(const float (&v)[8]) { u32x4 w; w.x = cvt_pk_bf16(v[0], v[1]); w.y = cvt_pk_bf16(v[2], v[3]); w.z = cvt_pk_bf16(v[4], v[5]); w.w = cvt_pk_bf16(v[6], v[7]); return w; }
; __device__ __forceinline__ void r3_item(const Args& a, int L, int item, LAS unsigned char* lds) {
;     ...
;     { const int mat = tid >> 8, i = (tid >> 2) & 63, g = tid & 3;
;         const int col = mat == 0 ? (hl < 4 ? GQ + hl * 64 : RQ + (hl - 4) * 64) : (hl < 4 ? GK + hl * 64 : RK + (hl - 4) * 64);
;         float va[8], vb[8]; load_qk16(a, proj + (R0 + i) * LD + col, hl, c * 64 + i, g, va, vb);
;         const float sg = mat == 0 ? 1.f : -1.f;
; #pragma unroll
;         for (int dir = 0; dir < 2; ++dir) { float ta[8], tb[8];
; #pragma unroll
;             for (int e = 0; e < 8; ++e) { ta[e] = va[e] * __expf(sg * cum[(dir * 64 + i) * 64 + g * 8 + e]); tb[e] = vb[e] * __expf(sg * cum[(dir * 64 + i) * 64 + 32 + g * 8 + e]); }
;             LAS bf16_t* dst = QK + ((dir * 2 + mat) * 64 + i) * PT;
;             *(LAS u32x4*)(dst + g * 8) = pack8(ta); *(LAS u32x4*)(dst + 32 + g * 8) = pack8(tb); } }
;     { const int j = tid >> 3, vg = tid & 7; const int vcol = hl < 4 ? GV + hl * 128 : RV + (hl - 4) * 128;
;         const bf16_t* vp = proj + (R0 + j) * LD + vcol + vg * 16;
; #pragma unroll
;         for (int q = 0; q < 2; ++q) { const u32x4 w = *(const u32x4*)(vp + q * 8); const int v0 = vg * 16 + q * 8;
;             VT[(v0 + 0) * PT + j] = (bf16_t)(w.x & 0xffff); VT[(v0 + 1) * PT + j] = (bf16_t)(w.x >> 16); VT[(v0 + 2) * PT + j] = (bf16_t)(w.y & 0xffff); VT[(v0 + 3) * PT + j] = (bf16_t)(w.y >> 16);
;             VT[(v0 + 4) * PT + j] = (bf16_t)(w.z & 0xffff); VT[(v0 + 5) * PT + j] = (bf16_t)(w.z >> 16); VT[(v0 + 6) * PT + j] = (bf16_t)(w.w & 0xffff); VT[(v0 + 7) * PT + j] = (bf16_t)(w.w >> 16); } }
;     ...
;         bf16x8 stf[2][4];
; #pragma unroll
;         for (int dir = 0; dir < 2; ++dir) { const bf16_t* stp = (const bf16_t*)(a.ws + WS_ST) + (size_t)seqidx(b, hl, dir, c) * 8192 + (vt * 32 + r32) * 64 + hi * 8;
; #pragma unroll
;             for (int ks = 0; ks < 4; ++ks) stf[dir][ks] = *(const bf16x8*)(stp + ks * 16); }
.LBB0_116:
	v_lshlrev_b32_e32 v16, 8, v21
	v_lshlrev_b32_e32 v17, 2, v22
	v_add3_u32 v16, 0, v16, v17
	ds_read_b128 v[26:29], v16
	ds_read_b128 v[30:33], v16 offset:16
	ds_read_b128 v[34:37], v16 offset:128
	ds_read_b128 v[38:41], v16 offset:144
	v_lshrrev_b32_e32 v17, 2, v24
	s_mov_b32 s5, 0xfffffc0
	s_waitcnt lgkmcnt(3)
	v_mul_f32_e32 v22, v20, v26
	s_waitcnt lgkmcnt(1)
	v_mul_f32_e32 v26, v20, v35
	v_mul_f32_e32 v26, 0x3fb8aa3b, v26
	v_exp_f32_e32 v26, v26
	v_mul_f32_e32 v23, v20, v34
	v_mul_f32_e32 v25, v20, v27
	v_mul_f32_e32 v27, v20, v36
	v_mul_f32_e32 v34, v11, v26
	v_mul_f32_e32 v26, v20, v28
	v_mul_f32_e32 v28, v20, v29
	v_mul_f32_e32 v29, v20, v37
	v_mul_f32_e32 v26, 0x3fb8aa3b, v26
	v_mul_f32_e32 v27, 0x3fb8aa3b, v27
	v_mul_f32_e32 v28, 0x3fb8aa3b, v28
	v_mul_f32_e32 v29, 0x3fb8aa3b, v29
	v_exp_f32_e32 v26, v26
	v_exp_f32_e32 v27, v27
	v_exp_f32_e32 v28, v28
	v_exp_f32_e32 v29, v29
	v_mul_f32_e32 v35, v14, v26
	v_mul_f32_e32 v36, v8, v27
	v_mul_f32_e32 v27, v15, v28
	v_mul_f32_e32 v37, v9, v29
	v_mul_f32_e32 v26, v20, v30
	s_waitcnt lgkmcnt(0)
	v_mul_f32_e32 v28, v20, v38
	v_mul_f32_e32 v29, v20, v31
	v_mul_f32_e32 v26, 0x3fb8aa3b, v26
	v_mul_f32_e32 v28, 0x3fb8aa3b, v28
	v_mul_f32_e32 v29, 0x3fb8aa3b, v29
	v_exp_f32_e32 v26, v26
	v_exp_f32_e32 v28, v28
	v_exp_f32_e32 v29, v29
	v_mul_f32_e32 v22, 0x3fb8aa3b, v22
	v_mul_f32_e32 v31, v12, v26
	v_mul_f32_e32 v38, v2, v28
	v_mul_f32_e32 v28, v13, v29
	v_mul_f32_e32 v26, v20, v32
	v_mul_f32_e32 v29, v20, v40
	v_mul_f32_e32 v32, v20, v33
	v_mul_f32_e32 v29, 0x3fb8aa3b, v29
	v_mul_f32_e32 v32, 0x3fb8aa3b, v32
	v_mul_f32_e32 v25, 0x3fb8aa3b, v25
	v_mul_f32_e32 v30, v20, v39
	v_mul_f32_e32 v26, 0x3fb8aa3b, v26
	v_exp_f32_e32 v29, v29
	v_exp_f32_e32 v32, v32
	v_mul_f32_e32 v33, v20, v41
	v_exp_f32_e32 v22, v22
	v_mul_f32_e32 v23, 0x3fb8aa3b, v23
	v_exp_f32_e32 v25, v25
	v_mul_f32_e32 v30, 0x3fb8aa3b, v30
	v_exp_f32_e32 v26, v26
	v_mul_f32_e32 v33, 0x3fb8aa3b, v33
	v_exp_f32_e32 v23, v23
	v_exp_f32_e32 v30, v30
	v_exp_f32_e32 v33, v33
	v_and_or_b32 v21, v17, s5, v21
	v_mul_f32_e32 v40, v6, v29
	v_mul_f32_e32 v29, v5, v32
	v_mul_lo_u32 v21, v21, s81
	v_mul_f32_e32 v22, v18, v22
	v_mul_f32_e32 v25, v19, v25
	v_mul_f32_e32 v39, v4, v26
	v_cvt_pk_bf16_f32 v26, v22, v25
	v_cvt_pk_bf16_f32 v27, v35, v27
	v_cvt_pk_bf16_f32 v28, v31, v28
	v_cvt_pk_bf16_f32 v29, v39, v29
	v_add3_u32 v0, 0, v21, v0
	v_mul_f32_e32 v23, v10, v23
	v_mul_f32_e32 v30, v3, v30
	v_mul_f32_e32 v32, v7, v33
	ds_write_b128 v0, v[26:29] offset:51200
	v_cvt_pk_bf16_f32 v26, v23, v34
	v_cvt_pk_bf16_f32 v27, v36, v37
	v_cvt_pk_bf16_f32 v28, v38, v30
	v_cvt_pk_bf16_f32 v29, v40, v32
	ds_write_b128 v0, v[26:29] offset:51264
	ds_read_b128 v[26:29], v16 offset:16384
	ds_read_b128 v[30:33], v16 offset:16400
	ds_read_b128 v[34:37], v16 offset:16512
	ds_read_b128 v[38:41], v16 offset:16528
	v_add_u32_e32 v0, 0xc800, v0
	s_lshl_b32 s5, s28, 7
	s_waitcnt lgkmcnt(3)
	v_mul_f32_e32 v21, v20, v26
	s_waitcnt lgkmcnt(1)
	v_mul_f32_e32 v16, v20, v34
	v_mul_f32_e32 v22, v20, v27
	v_mul_f32_e32 v23, v20, v35
	v_mul_f32_e32 v21, 0x3fb8aa3b, v21
	v_mul_f32_e32 v16, 0x3fb8aa3b, v16
	v_mul_f32_e32 v22, 0x3fb8aa3b, v22
	v_mul_f32_e32 v23, 0x3fb8aa3b, v23
	v_exp_f32_e32 v21, v21
	v_exp_f32_e32 v16, v16
	v_exp_f32_e32 v22, v22
	v_exp_f32_e32 v23, v23
	v_mul_f32_e32 v18, v18, v21
	v_mul_f32_e32 v10, v10, v16
	v_mul_f32_e32 v16, v19, v22
	v_mul_f32_e32 v11, v11, v23
	v_mul_f32_e32 v19, v20, v28
	v_mul_f32_e32 v21, v20, v36
	v_mul_f32_e32 v22, v20, v29
	v_mul_f32_e32 v23, v20, v37
	v_mul_f32_e32 v19, 0x3fb8aa3b, v19
	v_mul_f32_e32 v21, 0x3fb8aa3b, v21
	v_mul_f32_e32 v22, 0x3fb8aa3b, v22
	v_mul_f32_e32 v23, 0x3fb8aa3b, v23
	v_exp_f32_e32 v19, v19
	v_exp_f32_e32 v21, v21
	v_exp_f32_e32 v22, v22
	v_exp_f32_e32 v23, v23
	v_mul_f32_e32 v14, v14, v19
	v_mul_f32_e32 v8, v8, v21
	v_mul_f32_e32 v15, v15, v22
	v_mul_f32_e32 v9, v9, v23
	v_mul_f32_e32 v19, v20, v30
	s_waitcnt lgkmcnt(0)
	v_mul_f32_e32 v21, v20, v38
	v_mul_f32_e32 v22, v20, v31
	v_mul_f32_e32 v23, v20, v39
	v_mul_f32_e32 v19, 0x3fb8aa3b, v19
	v_mul_f32_e32 v21, 0x3fb8aa3b, v21
	v_mul_f32_e32 v22, 0x3fb8aa3b, v22
	v_mul_f32_e32 v23, 0x3fb8aa3b, v23
	v_exp_f32_e32 v19, v19
	v_exp_f32_e32 v21, v21
	v_exp_f32_e32 v22, v22
	v_exp_f32_e32 v23, v23
	v_mul_f32_e32 v12, v12, v19
	v_mul_f32_e32 v19, v2, v21
	v_mul_f32_e32 v13, v13, v22
	v_mul_f32_e32 v21, v3, v23
	v_mul_f32_e32 v2, v20, v32
	v_mul_f32_e32 v3, v20, v40
	v_mul_f32_e32 v22, v20, v33
	v_mul_f32_e32 v20, v20, v41
	v_mul_f32_e32 v2, 0x3fb8aa3b, v2
	v_mul_f32_e32 v3, 0x3fb8aa3b, v3
	v_mul_f32_e32 v22, 0x3fb8aa3b, v22
	v_mul_f32_e32 v20, 0x3fb8aa3b, v20
	v_exp_f32_e32 v2, v2
	v_exp_f32_e32 v3, v3
	v_exp_f32_e32 v22, v22
	v_exp_f32_e32 v20, v20
	v_mul_f32_e32 v23, v4, v2
	v_mul_f32_e32 v6, v6, v3
	v_mul_f32_e32 v5, v5, v22
	v_mul_f32_e32 v7, v7, v20
	v_cvt_pk_bf16_f32 v2, v18, v16
	v_cvt_pk_bf16_f32 v3, v14, v15
	v_cvt_pk_bf16_f32 v4, v12, v13
	v_ashrrev_i32_e32 v20, 3, v24
	v_cvt_pk_bf16_f32 v5, v23, v5
	ds_write_b128 v0, v[2:5] offset:18432
	v_cvt_pk_bf16_f32 v2, v10, v11
	v_cvt_pk_bf16_f32 v3, v8, v9
	v_cvt_pk_bf16_f32 v4, v19, v21
	v_ashrrev_i32_e32 v21, 31, v20
	v_cvt_pk_bf16_f32 v5, v6, v7
	ds_write_b128 v0, v[2:5] offset:18496
	v_lshl_add_u64 v[18:19], s[0:1], 0, v[20:21]
	v_mov_b64_e32 v[2:3], s[22:23]
	s_or_b32 s7, s5, 0xe00
	s_add_i32 s24, s5, 0x1200
	v_mad_u64_u32 v[22:23], s[0:1], v18, s79, v[2:3]
	s_and_b64 s[10:11], s[2:3], exec
	v_mov_b32_e32 v0, v23
	s_cselect_b32 s7, s7, s24
	v_mad_u64_u32 v[2:3], s[0:1], v19, s79, v[0:1]
	v_lshlrev_b32_e32 v0, 4, v24
	v_mov_b32_e32 v23, v2
	s_lshl_b32 s24, s7, 1
	v_and_b32_e32 v21, 0x70, v0
	v_lshl_add_u64 v[2:3], v[22:23], 0, s[24:25]
	v_lshlrev_b32_e32 v0, 1, v21
	v_lshl_add_u64 v[6:7], v[2:3], 0, v[0:1]
	global_load_dwordx4 v[2:5], v[6:7], off
	global_load_dwordx4 v[112:115], v[6:7], off offset:16
	v_and_b32_e32 v106, 31, v24
	v_bfe_u32 v107, v24, 5, 1
	v_lshlrev_b32_e32 v106, 7, v106
	v_lshl_or_b32 v106, v107, 4, v106
	v_bfe_u32 v107, v24, 6, 2
	s_lshr_b32 s100, s15, 6
	s_lshl_b32 s100, s100, 7
	s_and_b32 s101, s15, 63
	s_or_b32 s100, s100, s101
	v_lshl_or_b32 v106, v107, 12, v106
	s_lshl_b32 s100, s100, 14
	s_add_u32 s100, s8, s100
	s_addc_u32 s101, s9, 0
	global_load_dwordx4 v[72:75], v106, s[100:101]
	global_load_dwordx4 v[76:79], v106, s[100:101] offset:32
	global_load_dwordx4 v[80:83], v106, s[100:101] offset:64
	global_load_dwordx4 v[84:87], v106, s[100:101] offset:96
	s_add_u32 s100, s100, 0x100000
	s_addc_u32 s101, s101, 0
	global_load_dwordx4 v[88:91], v106, s[100:101]
	global_load_dwordx4 v[92:95], v106, s[100:101] offset:32
	global_load_dwordx4 v[96:99], v106, s[100:101] offset:64
	global_load_dwordx4 v[100:103], v106, s[100:101] offset:96
	v_mul_u32_u24_e32 v8, 0x90, v21
	v_lshlrev_b32_e32 v9, 1, v20
	v_add3_u32 v8, 0, v8, v9
	s_waitcnt vmcnt(8) lgkmcnt(0)
; #define LAS __attribute__((address_space(3)))
; __device__ __forceinline__ unsigned cvt_pk_bf16(float lo, float hi) { unsigned r; asm volatile("v_cvt_pk_bf16_f32 %0, %1, %2" : "=v"(r) : "v"(lo), "v"(hi)); return r; }
; __device__ __forceinline__ void r3_item(const Args& a, int L, int item, LAS unsigned char* lds) {
;     ...
;         for (int q = 0; q < 2; ++q) { const u32x4 w = *(const u32x4*)(vp + q * 8); const int v0 = vg * 16 + q * 8;
;             VT[(v0 + 0) * PT + j] = (bf16_t)(w.x & 0xffff); VT[(v0 + 1) * PT + j] = (bf16_t)(w.x >> 16); VT[(v0 + 2) * PT + j] = (bf16_t)(w.y & 0xffff); VT[(v0 + 3) * PT + j] = (bf16_t)(w.y >> 16);
;             VT[(v0 + 4) * PT + j] = (bf16_t)(w.z & 0xffff); VT[(v0 + 5) * PT + j] = (bf16_t)(w.z >> 16); VT[(v0 + 6) * PT + j] = (bf16_t)(w.w & 0xffff); VT[(v0 + 7) * PT + j] = (bf16_t)(w.w >> 16); } }
;     __syncthreads();
;     { const int dir = wid >> 2, it = (wid >> 1) & 1, jt = wid & 1; f32x16 sc = f32x16{};
;         const LAS bf16_t* Qt = QK + ((dir * 2 + 0) * 64) * PT; const LAS bf16_t* Kt = QK + ((dir * 2 + 1) * 64) * PT;
; #pragma unroll
;         for (int ks = 0; ks < 4; ++ks) { const bf16x8 av = *(const LAS bf16x8*)(Kt + (jt * 32 + r32) * PT + ks * 16 + hi * 8), bv = *(const LAS bf16x8*)(Qt + (it * 32 + r32) * PT + ks * 16 + hi * 8);
;             sc = __builtin_amdgcn_mfma_f32_32x32x16_bf16(av, bv, sc, 0, 0, 0); }
;         const int i = it * 32 + r32;
; #pragma unroll
;         for (int g4 = 0; g4 < 4; ++g4) { float v[4];
; #pragma unroll
;             for (int e = 0; e < 4; ++e) { const int j = jt * 32 + 8 * g4 + 4 * hi + e; const bool keep = dir == 0 ? (j <= i) : (j >= i); v[e] = keep ? sc[g4 * 4 + e] : 0.f; }
;             u32x2 w; w.x = cvt_pk_bf16(v[0], v[1]); w.y = cvt_pk_bf16(v[2], v[3]);
;             *(LAS u32x2*)(P + (dir * 64 + i) * PT + jt * 32 + 8 * g4 + 4 * hi) = w; } }
	ds_write_b16 v8, v2 offset:32768
	ds_write_b16_d16_hi v8, v2 offset:32912
	ds_write_b16 v8, v3 offset:33056
	ds_write_b16_d16_hi v8, v3 offset:33200
	ds_write_b16 v8, v4 offset:33344
	ds_write_b16_d16_hi v8, v4 offset:33488
	ds_write_b16 v8, v5 offset:33632
	ds_write_b16_d16_hi v8, v5 offset:33776
	v_ashrrev_i32_e32 v42, 6, v24
	v_and_b32_e32 v44, 1, v42
	v_and_b32_e32 v66, 31, v24
	v_lshlrev_b32_e32 v45, 5, v44
	v_bfe_u32 v25, v24, 5, 1
	ds_write_b16 v8, v112 offset:33920
	ds_write_b16_d16_hi v8, v112 offset:34064
	ds_write_b16 v8, v113 offset:34208
	ds_write_b16_d16_hi v8, v113 offset:34352
	ds_write_b16 v8, v114 offset:34496
	ds_write_b16_d16_hi v8, v114 offset:34640
	ds_write_b16 v8, v115 offset:34784
	ds_write_b16_d16_hi v8, v115 offset:34928
	v_ashrrev_i32_e32 v43, 8, v24
	s_movk_i32 s0, 0x4800
	v_or_b32_e32 v2, v45, v66
	v_mad_i32_i24 v6, v43, s0, 0
	v_mul_u32_u24_e32 v2, 0x90, v2
	v_lshlrev_b32_e32 v24, 4, v25
	v_add3_u32 v34, v6, v2, v24
	s_waitcnt lgkmcnt(0)
	s_barrier
	ds_read_b128 v[2:5], v34 offset:60416
	v_and_or_b32 v46, v17, 32, v66
	v_mul_u32_u24_e32 v7, 0x90, v46
	v_add3_u32 v38, v6, v7, v24
	ds_read_b128 v[6:9], v38 offset:51200
	ds_read_b128 v[26:29], v34 offset:60448
	ds_read_b128 v[30:33], v38 offset:51232
	s_waitcnt lgkmcnt(2)
	v_mfma_f32_32x32x16_bf16 v[2:17], v[2:5], v[6:9], 0
	v_lshlrev_b32_e32 v67, 2, v25
	v_readlane_b32 s7, v253, 24
	v_and_b32_e32 v68, 3, v42
	s_lshl_b32 s0, s4, 10
	s_or_b32 s0, s5, s0
	v_lshlrev_b32_e32 v69, 5, v43
	s_or_b32 s0, s0, s6
	s_waitcnt lgkmcnt(0)
	v_mfma_f32_32x32x16_bf16 v[2:17], v[26:29], v[30:33], v[2:17]
	ds_read_b128 v[26:29], v34 offset:60480
	ds_read_b128 v[30:33], v38 offset:51264
	ds_read_b128 v[34:37], v34 offset:60512
	ds_read_b128 v[38:41], v38 offset:51296
	s_ashr_i32 s1, s0, 31
	s_movk_i32 s4, 0x210
	s_waitcnt lgkmcnt(2)
	v_mfma_f32_32x32x16_bf16 v[2:17], v[26:29], v[30:33], v[2:17]
	v_lshl_or_b32 v27, v43, 6, v46
	v_lshlrev_b32_e32 v26, 3, v25
	v_or_b32_e32 v25, v45, v67
	v_mul_lo_u32 v27, v27, s81
	v_add_u32_e32 v27, s7, v27
	v_lshlrev_b32_e32 v28, 6, v44
	v_cmp_le_u32_e32 vcc, v25, v46
	s_waitcnt lgkmcnt(0)
	v_mfma_f32_32x32x16_bf16 v[2:17], v[34:37], v[38:41], v[2:17]
	v_add3_u32 v26, v27, v28, v26
	v_cndmask_b32_e64 v27, 0, 1, vcc
	v_cmp_ge_u32_e32 vcc, v25, v46
	s_nop 1
	v_cndmask_b32_e64 v28, 0, 1, vcc
	v_cndmask_b32_e64 v27, v28, v27, s[38:39]
	v_and_b32_e32 v27, 1, v27
	v_cmp_eq_u32_e32 vcc, 1, v27
	v_or_b32_e32 v27, 1, v25
	s_nop 1
	v_cndmask_b32_e32 v2, 0, v2, vcc
	v_cmp_lt_u32_e32 vcc, v25, v46
	s_nop 1
	v_cndmask_b32_e64 v28, 0, 1, vcc
	v_cmp_ge_u32_e32 vcc, v27, v46
	s_nop 1
	v_cndmask_b32_e64 v27, 0, 1, vcc
	v_cndmask_b32_e64 v27, v27, v28, s[38:39]
	v_and_b32_e32 v27, 1, v27
	v_cmp_eq_u32_e32 vcc, 1, v27
	v_or_b32_e32 v27, 2, v25
	s_nop 0
	v_cndmask_b32_e32 v3, 0, v3, vcc
	v_cmp_le_u32_e32 vcc, v27, v46
	v_cvt_pk_bf16_f32 v2, v2, v3
	s_nop 1
	v_cndmask_b32_e64 v28, 0, 1, vcc
	v_cmp_ge_u32_e32 vcc, v27, v46
	s_nop 1
	v_cndmask_b32_e64 v27, 0, 1, vcc
	v_cndmask_b32_e64 v27, v27, v28, s[38:39]
	v_and_b32_e32 v27, 1, v27
	v_cmp_eq_u32_e32 vcc, 1, v27
	v_or_b32_e32 v27, 3, v25
	s_nop 0
	v_cndmask_b32_e32 v4, 0, v4, vcc
	v_cmp_le_u32_e32 vcc, v27, v46
	s_nop 1
	v_cndmask_b32_e64 v28, 0, 1, vcc
	v_cmp_ge_u32_e32 vcc, v27, v46
	s_nop 1
	v_cndmask_b32_e64 v27, 0, 1, vcc
	v_cndmask_b32_e64 v27, v27, v28, s[38:39]
	v_and_b32_e32 v27, 1, v27
	v_cmp_eq_u32_e32 vcc, 1, v27
	s_nop 1
	v_cndmask_b32_e32 v5, 0, v5, vcc
	v_cvt_pk_bf16_f32 v3, v4, v5
	ds_write_b64 v26, v[2:3]
	v_or_b32_e32 v2, 8, v25
	v_cmp_le_u32_e32 vcc, v2, v46
	s_nop 1
	v_cndmask_b32_e64 v3, 0, 1, vcc
	v_cmp_ge_u32_e32 vcc, v2, v46
	s_nop 1
	v_cndmask_b32_e64 v2, 0, 1, vcc
	v_cndmask_b32_e64 v2, v2, v3, s[38:39]
	v_and_b32_e32 v2, 1, v2
	v_cmp_eq_u32_e32 vcc, 1, v2
	v_or_b32_e32 v3, 9, v25
	s_nop 0
	v_cndmask_b32_e32 v2, 0, v6, vcc
	v_cmp_le_u32_e32 vcc, v3, v46
	s_nop 1
	v_cndmask_b32_e64 v4, 0, 1, vcc
	v_cmp_ge_u32_e32 vcc, v3, v46
	s_nop 1
	v_cndmask_b32_e64 v3, 0, 1, vcc
	v_cndmask_b32_e64 v3, v3, v4, s[38:39]
	v_and_b32_e32 v3, 1, v3
	v_cmp_eq_u32_e32 vcc, 1, v3
	v_or_b32_e32 v4, 10, v25
	s_nop 0
	v_cndmask_b32_e32 v3, 0, v7, vcc
	v_cmp_le_u32_e32 vcc, v4, v46
	v_cvt_pk_bf16_f32 v2, v2, v3
	s_nop 1
	v_cndmask_b32_e64 v5, 0, 1, vcc
	v_cmp_ge_u32_e32 vcc, v4, v46
	s_nop 1
	v_cndmask_b32_e64 v4, 0, 1, vcc
	v_cndmask_b32_e64 v4, v4, v5, s[38:39]
	v_and_b32_e32 v4, 1, v4
	v_cmp_eq_u32_e32 vcc, 1, v4
	v_or_b32_e32 v5, 11, v25
	s_nop 0
	v_cndmask_b32_e32 v4, 0, v8, vcc
	v_cmp_le_u32_e32 vcc, v5, v46
	s_nop 1
	v_cndmask_b32_e64 v6, 0, 1, vcc
	v_cmp_ge_u32_e32 vcc, v5, v46
	s_nop 1
	v_cndmask_b32_e64 v5, 0, 1, vcc
	v_cndmask_b32_e64 v5, v5, v6, s[38:39]
	v_and_b32_e32 v5, 1, v5
	v_cmp_eq_u32_e32 vcc, 1, v5
	s_nop 1
	v_cndmask_b32_e32 v5, 0, v9, vcc
	v_cvt_pk_bf16_f32 v3, v4, v5
	ds_write_b64 v26, v[2:3] offset:16
	v_or_b32_e32 v2, 16, v25
	v_cmp_le_u32_e32 vcc, v2, v46
	s_nop 1
	v_cndmask_b32_e64 v3, 0, 1, vcc
	v_cmp_ge_u32_e32 vcc, v2, v46
	s_nop 1
	v_cndmask_b32_e64 v2, 0, 1, vcc
	v_cndmask_b32_e64 v2, v2, v3, s[38:39]
	v_and_b32_e32 v2, 1, v2
	v_cmp_eq_u32_e32 vcc, 1, v2
	v_or_b32_e32 v3, 17, v25
	s_nop 0
	v_cndmask_b32_e32 v2, 0, v10, vcc
	v_cmp_le_u32_e32 vcc, v3, v46
	s_nop 1
	v_cndmask_b32_e64 v4, 0, 1, vcc
	v_cmp_ge_u32_e32 vcc, v3, v46
	s_nop 1
	v_cndmask_b32_e64 v3, 0, 1, vcc
	v_cndmask_b32_e64 v3, v3, v4, s[38:39]
	v_and_b32_e32 v3, 1, v3
	v_cmp_eq_u32_e32 vcc, 1, v3
	v_or_b32_e32 v4, 18, v25
	s_nop 0
	v_cndmask_b32_e32 v3, 0, v11, vcc
	v_cmp_le_u32_e32 vcc, v4, v46
	v_cvt_pk_bf16_f32 v2, v2, v3
	s_nop 1
	v_cndmask_b32_e64 v5, 0, 1, vcc
	v_cmp_ge_u32_e32 vcc, v4, v46
	s_nop 1
; #define LAS __attribute__((address_space(3)))
; __device__ __forceinline__ unsigned cvt_pk_bf16(float lo, float hi) { unsigned r; asm volatile("v_cvt_pk_bf16_f32 %0, %1, %2" : "=v"(r) : "v"(lo), "v"(hi)); return r; }
; __device__ __forceinline__ int crow(int r, int hi) { return (r & 3) + 8 * (r >> 2) + 4 * hi; }
; __device__ __forceinline__ int crow(int r, int hi) { return (r & 3) + 8 * (r >> 2) + 4 * hi; }
; __device__ __forceinline__ void r3_item(const Args& a, int L, int item, LAS unsigned char* lds) {
;     ...
;         for (int g4 = 0; g4 < 4; ++g4) { float v[4];
; #pragma unroll
;             for (int e = 0; e < 4; ++e) { const int j = jt * 32 + 8 * g4 + 4 * hi + e; const bool keep = dir == 0 ? (j <= i) : (j >= i); v[e] = keep ? sc[g4 * 4 + e] : 0.f; }
;             u32x2 w; w.x = cvt_pk_bf16(v[0], v[1]); w.y = cvt_pk_bf16(v[2], v[3]);
;             *(LAS u32x2*)(P + (dir * 64 + i) * PT + jt * 32 + 8 * g4 + 4 * hi) = w; } }
;     __syncthreads();
;     { const int it = wid >> 2, vt = wid & 3; f32x16 acc = f32x16{};
;         bf16x8 stf[2][4];
; #pragma unroll
;         for (int dir = 0; dir < 2; ++dir) { const bf16_t* stp = (const bf16_t*)(a.ws + WS_ST) + (size_t)seqidx(b, hl, dir, c) * 8192 + (vt * 32 + r32) * 64 + hi * 8;
; #pragma unroll
;             for (int ks = 0; ks < 4; ++ks) stf[dir][ks] = *(const bf16x8*)(stp + ks * 16); }
; #pragma unroll
;         for (int dir = 0; dir < 2; ++dir) { const LAS bf16_t* Qt = QK + ((dir * 2 + 0) * 64) * PT;
; #pragma unroll
;             for (int ks = 0; ks < 4; ++ks) { const bf16x8 av = *(const LAS bf16x8*)(P + (dir * 64 + it * 32 + r32) * PT + ks * 16 + hi * 8), bv = *(const LAS bf16x8*)(VT + (vt * 32 + r32) * PT + ks * 16 + hi * 8);
;                 acc = __builtin_amdgcn_mfma_f32_32x32x16_bf16(av, bv, acc, 0, 0, 0); }
; #pragma unroll
;             for (int ks = 0; ks < 4; ++ks) { const bf16x8 av = *(const LAS bf16x8*)(Qt + (it * 32 + r32) * PT + ks * 16 + hi * 8), bv = stf[dir][ks];
;                 acc = __builtin_amdgcn_mfma_f32_32x32x16_bf16(av, bv, acc, 0, 0, 0); } }
;         __syncthreads();
;         LAS float* OL = (LAS float*)(lds + L_OL);
; #pragma unroll
;         for (int r = 0; r < 16; ++r) OL[(it * 32 + crow(r, hi)) * OLP + vt * 32 + r32] = acc[r]; }
;     ...
;         const bf16_t* gp = proj + (R0 + row) * LD + gcol; const u32x4 g0 = *(const u32x4*)gp, g1 = *(const u32x4*)(gp + 8);
	v_cndmask_b32_e64 v4, 0, 1, vcc
	v_cndmask_b32_e64 v4, v4, v5, s[38:39]
	v_and_b32_e32 v4, 1, v4
	v_cmp_eq_u32_e32 vcc, 1, v4
	v_or_b32_e32 v5, 19, v25
	s_nop 0
	v_cndmask_b32_e32 v4, 0, v12, vcc
	v_cmp_le_u32_e32 vcc, v5, v46
	s_nop 1
	v_cndmask_b32_e64 v6, 0, 1, vcc
	v_cmp_ge_u32_e32 vcc, v5, v46
	s_nop 1
	v_cndmask_b32_e64 v5, 0, 1, vcc
	v_cndmask_b32_e64 v5, v5, v6, s[38:39]
	v_and_b32_e32 v5, 1, v5
	v_cmp_eq_u32_e32 vcc, 1, v5
	s_nop 1
	v_cndmask_b32_e32 v5, 0, v13, vcc
	v_cvt_pk_bf16_f32 v3, v4, v5
	ds_write_b64 v26, v[2:3] offset:32
	v_or_b32_e32 v2, 24, v25
	v_cmp_le_u32_e32 vcc, v2, v46
	s_nop 1
	v_cndmask_b32_e64 v3, 0, 1, vcc
	v_cmp_ge_u32_e32 vcc, v2, v46
	s_nop 1
	v_cndmask_b32_e64 v2, 0, 1, vcc
	v_cndmask_b32_e64 v2, v2, v3, s[38:39]
	v_and_b32_e32 v2, 1, v2
	v_cmp_eq_u32_e32 vcc, 1, v2
	v_or_b32_e32 v3, 25, v25
	s_nop 0
	v_cndmask_b32_e32 v2, 0, v14, vcc
	v_cmp_le_u32_e32 vcc, v3, v46
	s_nop 1
	v_cndmask_b32_e64 v4, 0, 1, vcc
	v_cmp_ge_u32_e32 vcc, v3, v46
	s_nop 1
	v_cndmask_b32_e64 v3, 0, 1, vcc
	v_cndmask_b32_e64 v3, v3, v4, s[38:39]
	v_and_b32_e32 v3, 1, v3
	v_cmp_eq_u32_e32 vcc, 1, v3
	v_or_b32_e32 v4, 26, v25
	s_nop 0
	v_cndmask_b32_e32 v3, 0, v15, vcc
	v_cmp_le_u32_e32 vcc, v4, v46
	v_cvt_pk_bf16_f32 v2, v2, v3
	s_nop 1
	v_cndmask_b32_e64 v5, 0, 1, vcc
	v_cmp_ge_u32_e32 vcc, v4, v46
	s_nop 1
	v_cndmask_b32_e64 v4, 0, 1, vcc
	v_cndmask_b32_e64 v4, v4, v5, s[38:39]
	v_and_b32_e32 v4, 1, v4
	v_cmp_eq_u32_e32 vcc, 1, v4
	v_or_b32_e32 v5, 27, v25
	v_mov_b32_e32 v25, v1
	v_cndmask_b32_e32 v4, 0, v16, vcc
	v_cmp_le_u32_e32 vcc, v5, v46
	s_nop 1
	v_cndmask_b32_e64 v6, 0, 1, vcc
	v_cmp_ge_u32_e32 vcc, v5, v46
	s_nop 1
	v_cndmask_b32_e64 v5, 0, 1, vcc
	v_cndmask_b32_e64 v5, v5, v6, s[38:39]
	v_and_b32_e32 v5, 1, v5
	v_cmp_eq_u32_e32 vcc, 1, v5
	v_lshl_or_b32 v6, v68, 5, v66
	v_mul_u32_u24_e32 v6, 0x90, v6
	v_cndmask_b32_e32 v5, 0, v17, vcc
	v_cvt_pk_bf16_f32 v3, v4, v5
	ds_write_b64 v26, v[2:3] offset:48
	v_lshlrev_b32_e32 v2, 7, v66
	v_lshl_or_b32 v2, v68, 12, v2
	v_mov_b32_e32 v3, v1
	v_lshl_add_u64 v[2:3], s[8:9], 0, v[2:3]
	v_lshl_add_u64 v[62:63], v[2:3], 0, v[24:25]
	v_or_b32_e32 v2, v69, v66
	v_mul_lo_u32 v25, v2, s81
	v_add3_u32 v70, s7, v24, v25
	s_lshl_b64 s[6:7], s[0:1], 14
	v_add3_u32 v50, 0, v6, v24
	v_lshl_add_u64 v[64:65], v[62:63], 0, s[6:7]
	s_waitcnt lgkmcnt(0)
	s_barrier
	ds_read_b128 v[2:5], v70
	ds_read_b128 v[26:29], v50 offset:32768
	ds_read_b128 v[30:33], v70 offset:32
	ds_read_b128 v[34:37], v50 offset:32800
	s_waitcnt lgkmcnt(0)
	v_mfma_f32_32x32x16_bf16 v[2:17], v[2:5], v[26:29], 0
	v_add3_u32 v71, 0, v25, v24
	s_or_b32 s0, s0, 64
	s_ashr_i32 s1, s0, 31
	s_lshl_b64 s[0:1], s[0:1], 14
	v_mfma_f32_32x32x16_bf16 v[2:17], v[30:33], v[34:37], v[2:17]
	ds_read_b128 v[30:33], v70 offset:64
	ds_read_b128 v[42:45], v50 offset:32832
	ds_read_b128 v[46:49], v70 offset:96
	ds_read_b128 v[50:53], v50 offset:32864
	ds_read_b128 v[54:57], v71 offset:51200
	ds_read_b128 v[58:61], v71 offset:51232
	s_waitcnt lgkmcnt(0)
	v_mfma_f32_32x32x16_bf16 v[2:17], v[30:33], v[42:45], v[2:17]
	v_mfma_f32_32x32x16_bf16 v[2:17], v[46:49], v[50:53], v[2:17]
	s_waitcnt vmcnt(0)
	v_mfma_f32_32x32x16_bf16 v[2:17], v[54:57], v[72:75], v[2:17]
	s_waitcnt lgkmcnt(0)
	v_mfma_f32_32x32x16_bf16 v[2:17], v[58:61], v[76:79], v[2:17]
	ds_read_b128 v[30:33], v71 offset:51264
	ds_read_b128 v[54:57], v71 offset:51296
	s_waitcnt lgkmcnt(0)
	v_mfma_f32_32x32x16_bf16 v[2:17], v[30:33], v[80:83], v[2:17]
	ds_read_b128 v[30:33], v70 offset:9216
	v_lshl_add_u64 v[46:47], v[62:63], 0, s[0:1]
	s_and_b64 s[0:1], s[2:3], exec
	s_movk_i32 s0, 0x1400
	s_cselect_b32 s0, 0x1000, s0
	s_or_b32 s0, s0, s5
	s_waitcnt vmcnt(0)
	v_mfma_f32_32x32x16_bf16 v[2:17], v[54:57], v[84:87], v[2:17]
	ds_read_b128 v[38:41], v70 offset:9248
	s_waitcnt lgkmcnt(1)
	v_mfma_f32_32x32x16_bf16 v[2:17], v[30:33], v[26:29], v[2:17]
	s_waitcnt lgkmcnt(0)
	v_mfma_f32_32x32x16_bf16 v[2:17], v[38:41], v[34:37], v[2:17]
	ds_read_b128 v[28:31], v70 offset:9280
	ds_read_b128 v[32:35], v70 offset:9312
	s_waitcnt lgkmcnt(0)
	v_mfma_f32_32x32x16_bf16 v[2:17], v[28:31], v[42:45], v[2:17]
	v_add_u32_e32 v44, 0xc800, v71
	ds_read_b128 v[36:39], v44 offset:18432
	ds_read_b128 v[40:43], v44 offset:18464
	v_mfma_f32_32x32x16_bf16 v[2:17], v[32:35], v[50:53], v[2:17]
	s_waitcnt vmcnt(0) lgkmcnt(0)
	v_mfma_f32_32x32x16_bf16 v[2:17], v[36:39], v[88:91], v[2:17]
	v_mfma_f32_32x32x16_bf16 v[2:17], v[40:43], v[92:95], v[2:17]
	ds_read_b128 v[28:31], v44 offset:18496
	ds_read_b128 v[36:39], v44 offset:18528
	s_waitcnt lgkmcnt(0)
	s_barrier
	v_or_b32_e32 v106, s0, v21
	v_lshlrev_b32_e32 v106, 1, v106
	v_mov_b32_e32 v107, 0
	v_lshl_add_u64 v[106:107], v[22:23], 0, v[106:107]
	global_load_dwordx4 v[108:111], v[106:107], off
	global_load_dwordx4 v[124:127], v[106:107], off offset:16
	v_mfma_f32_32x32x16_bf16 v[2:17], v[28:31], v[96:99], v[2:17]
	s_waitcnt vmcnt(2)
	v_mfma_f32_32x32x16_bf16 v[2:17], v[36:39], v[100:103], v[2:17]
	v_or_b32_e32 v24, v67, v69
	v_lshl_add_u32 v25, v68, 7, 0
	v_lshlrev_b32_e32 v26, 2, v66
	v_mul_lo_u32 v24, v24, s4
	v_add3_u32 v24, v25, v26, v24
	v_add_u32_e32 v25, 0xc800, v24
	s_nop 5
	ds_write2_b32 v25, v2, v3 offset1:132
	v_add_u32_e32 v2, 0xcc00, v24
	ds_write2_b32 v2, v4, v5 offset0:8 offset1:140
	v_add_u32_e32 v2, 0xd800, v24
	ds_write2_b32 v2, v6, v7 offset0:32 offset1:164
	v_add_u32_e32 v2, 0xdc00, v24
	ds_write2_b32 v2, v8, v9 offset0:40 offset1:172
	v_add_u32_e32 v2, 0xe800, v24
	ds_write2_b32 v2, v10, v11 offset0:64 offset1:196
	v_add_u32_e32 v2, 0xec00, v24
	ds_write2_b32 v2, v12, v13 offset0:72 offset1:204
	v_add_u32_e32 v2, 0xf800, v24
	ds_write2_b32 v2, v14, v15 offset0:96 offset1:228
	v_add_u32_e32 v2, 0xfc00, v24
	ds_write2_b32 v2, v16, v17 offset0:104 offset1:236
	v_or_b32_e32 v2, s0, v21
	v_lshlrev_b32_e32 v2, 1, v2
	v_mov_b32_e32 v3, v1
	v_lshl_add_u64 v[2:3], v[22:23], 0, v[2:3]
	s_waitcnt lgkmcnt(0)
	s_barrier
; #define LAS __attribute__((address_space(3)))
; __device__ __forceinline__ void r3_item(const Args& a, int L, int item, LAS unsigned char* lds) {
;     ...
;     { const int row = tid >> 3, seg = tid & 7; const LAS float* op = (const LAS float*)(lds + L_OL) + row * OLP + seg * 16; float ov[16]; float s = 0.f;
; #pragma unroll
;         for (int e = 0; e < 16; ++e) { ov[e] = op[e]; s += ov[e] * ov[e]; }
;         s += __shfl_xor(s, 1); s += __shfl_xor(s, 2); s += __shfl_xor(s, 4);
;         const float rs = rsqrtf(s * (1.0f / 128.0f) + EPS);
;         const int gcol = (hl < 4 ? GR + hl * 128 : RG + (hl - 4) * 128) + seg * 16;
;         const bf16_t* gp = proj + (R0 + row) * LD + gcol; const u32x4 g0 = *(const u32x4*)gp, g1 = *(const u32x4*)(gp + 8);
;         float gt[16] = {bflo(g0.x), bfhi(g0.x), bflo(g0.y), bfhi(g0.y), bflo(g0.z), bfhi(g0.z), bflo(g0.w), bfhi(g0.w), bflo(g1.x), bfhi(g1.x), bflo(g1.y), bfhi(g1.y), bflo(g1.z), bfhi(g1.z), bflo(g1.w), bfhi(g1.w)};
;         const float* hg = a.head_gain + (size_t)L * D + 1024 + hl * 128 + seg * 16;
	s_lshl_b32 s0, s28, 9
	s_add_u32 s0, s12, s0
	v_mul_lo_u32 v4, v20, s4
	v_lshlrev_b32_e32 v20, 2, v21
	s_addc_u32 s1, s13, 0
	v_mov_b32_e32 v21, v1
	v_add3_u32 v4, 0, v4, v20
	v_lshl_add_u64 v[38:39], s[0:1], 0, v[20:21]
	ds_read_b128 v[14:17], v4 offset:51200
	ds_read_b128 v[10:13], v4 offset:51216
	ds_read_b128 v[6:9], v4 offset:51232
	ds_read_b128 v[2:5], v4 offset:51248
	global_load_dwordx4 v[30:33], v[38:39], off
	s_waitcnt lgkmcnt(0)
	v_mul_f32_e32 v34, v15, v15
	v_fmac_f32_e32 v34, v14, v14
	v_fmac_f32_e32 v34, v16, v16
	v_fmac_f32_e32 v34, v17, v17
	v_fmac_f32_e32 v34, v10, v10
	v_fmac_f32_e32 v34, v11, v11
	v_fmac_f32_e32 v34, v12, v12
	v_fmac_f32_e32 v34, v13, v13
	v_pk_mul_f32 v[20:21], v[6:7], v[6:7]
	s_lshl_b32 s24, s28, 8
	v_add_f32_e32 v20, v34, v20
	v_add_f32_e32 v34, v20, v21
	v_pk_mul_f32 v[20:21], v[8:9], v[8:9]
	s_mov_b64 s[0:1], 0x21300800
	v_add_f32_e32 v20, v34, v20
	v_add_f32_e32 v34, v20, v21
	v_pk_mul_f32 v[20:21], v[2:3], v[2:3]
	s_add_i32 s15, s15, s87
	v_add_f32_e32 v20, v34, v20
	v_add_f32_e32 v34, v20, v21
	v_pk_mul_f32 v[20:21], v[4:5], v[4:5]
	s_add_i32 s14, s14, s87
	v_add_f32_e32 v20, v34, v20
	v_and_b32_e32 v34, 64, v208
	v_add_f32_e32 v20, v20, v21
	v_xor_b32_e32 v21, 1, v208
	v_add_u32_e32 v40, 64, v34
	v_cmp_lt_i32_e32 vcc, v21, v40
	global_load_dwordx4 v[34:37], v[38:39], off offset:16
	s_cmpk_gt_i32 s15, 0x3ff
	v_cndmask_b32_e32 v21, v208, v21, vcc
	v_lshlrev_b32_e32 v21, 2, v21
	ds_bpermute_b32 v21, v21, v20
	s_waitcnt lgkmcnt(0)
	v_add_f32_e32 v20, v20, v21
	v_xor_b32_e32 v21, 2, v208
	v_cmp_lt_i32_e32 vcc, v21, v40
	s_waitcnt vmcnt(0)
	v_mov_b32_e32 v22, v108
	v_mov_b32_e32 v23, v109
	v_mov_b32_e32 v24, v110
	v_mov_b32_e32 v25, v111
	v_mov_b32_e32 v26, v124
	v_mov_b32_e32 v27, v125
	v_mov_b32_e32 v28, v126
	v_mov_b32_e32 v29, v127
	v_and_b32_e32 v42, 0xffff0000, v22
	v_cndmask_b32_e32 v21, v208, v21, vcc
	v_lshlrev_b32_e32 v21, 2, v21
	ds_bpermute_b32 v21, v21, v20
	v_lshlrev_b32_e32 v44, 16, v23
	v_and_b32_e32 v46, 0xffff0000, v23
	v_lshlrev_b32_e32 v48, 16, v24
	v_and_b32_e32 v50, 0xffff0000, v24
	s_waitcnt lgkmcnt(0)
	v_add_f32_e32 v20, v20, v21
	v_xor_b32_e32 v21, 4, v208
	v_cmp_lt_i32_e32 vcc, v21, v40
	v_lshlrev_b32_e32 v40, 16, v22
	v_mul_f32_e32 v24, 0xbfb8aa3b, v40
	v_cndmask_b32_e32 v21, v208, v21, vcc
	v_lshlrev_b32_e32 v21, 2, v21
	ds_bpermute_b32 v21, v21, v20
	v_exp_f32_e32 v24, v24
	v_lshlrev_b32_e32 v52, 16, v25
	v_and_b32_e32 v54, 0xffff0000, v25
	v_mov_b32_e32 v25, v30
	s_waitcnt lgkmcnt(0)
; __device__ __forceinline__ unsigned cvt_pk_bf16(float lo, float hi) { unsigned r; asm volatile("v_cvt_pk_bf16_f32 %0, %1, %2" : "=v"(r) : "v"(lo), "v"(hi)); return r; }
; __device__ __forceinline__ float siluf(float x) { return x * __builtin_amdgcn_rcpf(1.f + __expf(-x)); }
; __device__ __forceinline__ void r3_item(const Args& a, int L, int item, LAS unsigned char* lds) {
;     ...
;         const float rs = rsqrtf(s * (1.0f / 128.0f) + EPS);
;         const int gcol = (hl < 4 ? GR + hl * 128 : RG + (hl - 4) * 128) + seg * 16;
;         const bf16_t* gp = proj + (R0 + row) * LD + gcol; const u32x4 g0 = *(const u32x4*)gp, g1 = *(const u32x4*)(gp + 8);
;         float gt[16] = {bflo(g0.x), bfhi(g0.x), bflo(g0.y), bfhi(g0.y), bflo(g0.z), bfhi(g0.z), bflo(g0.w), bfhi(g0.w), bflo(g1.x), bfhi(g1.x), bflo(g1.y), bfhi(g1.y), bflo(g1.z), bfhi(g1.z), bflo(g1.w), bfhi(g1.w)};
;         const float* hg = a.head_gain + (size_t)L * D + 1024 + hl * 128 + seg * 16;
;         float res[16];
; #pragma unroll
;         for (int e = 0; e < 16; ++e) res[e] = ov[e] * rs * hg[e] * siluf(gt[e]);
;         bf16_t* mp = (bf16_t*)(a.ws + WS_MRG) + (R0 + row) * D + 1024 + hl * 128 + seg * 16;
;         u32x4 w0, w1; w0.x = cvt_pk_bf16(res[0], res[1]); w0.y = cvt_pk_bf16(res[2], res[3]); w0.z = cvt_pk_bf16(res[4], res[5]); w0.w = cvt_pk_bf16(res[6], res[7]);
;         w1.x = cvt_pk_bf16(res[8], res[9]); w1.y = cvt_pk_bf16(res[10], res[11]); w1.z = cvt_pk_bf16(res[12], res[13]); w1.w = cvt_pk_bf16(res[14], res[15]);
;         *(u32x4*)mp = w0; *(u32x4*)(mp + 8) = w1; }
	v_add_f32_e32 v20, v20, v21
	v_fmamk_f32 v20, v20, 0x3c000000, v207
	v_mul_f32_e32 v21, 0x4b800000, v20
	v_cmp_gt_f32_e32 vcc, s34, v20
	v_lshlrev_b32_e32 v56, 16, v26
	v_and_b32_e32 v58, 0xffff0000, v26
	v_cndmask_b32_e32 v20, v20, v21, vcc
	v_rsq_f32_e32 v20, v20
	v_lshlrev_b32_e32 v60, 16, v27
	v_and_b32_e32 v62, 0xffff0000, v27
	v_lshlrev_b32_e32 v64, 16, v28
	v_mul_f32_e32 v21, 0x45800000, v20
	v_cndmask_b32_e32 v69, v20, v21, vcc
	global_load_dwordx4 v[20:23], v[38:39], off offset:32
	v_mul_f32_e32 v41, v14, v69
	v_add_f32_e32 v14, 1.0, v24
	v_rcp_f32_e32 v24, v14
	v_mul_f32_e32 v14, 0xbfb8aa3b, v42
	v_exp_f32_e32 v14, v14
	v_mul_f32_e32 v43, v15, v69
	v_pk_mul_f32 v[24:25], v[24:25], v[40:41]
	v_mul_f32_e32 v45, v16, v69
	v_add_f32_e32 v14, 1.0, v14
	v_rcp_f32_e32 v30, v14
	v_mul_f32_e32 v14, 0xbfb8aa3b, v44
	v_mul_f32_e32 v40, v24, v25
	v_exp_f32_e32 v24, v14
	v_pk_mul_f32 v[14:15], v[30:31], v[42:43]
	v_mul_f32_e32 v47, v17, v69
	v_mul_f32_e32 v30, v14, v15
	v_add_f32_e32 v14, 1.0, v24
	global_load_dwordx4 v[24:27], v[38:39], off offset:48
	v_rcp_f32_e32 v14, v14
	v_mul_f32_e32 v15, 0xbfb8aa3b, v46
	v_exp_f32_e32 v16, v15
	v_mov_b32_e32 v15, v32
	v_pk_mul_f32 v[14:15], v[14:15], v[44:45]
	v_mul_f32_e32 v49, v10, v69
	v_mul_f32_e32 v31, v14, v15
	v_add_f32_e32 v14, 1.0, v16
	v_rcp_f32_e32 v32, v14
	v_mul_f32_e32 v14, 0xbfb8aa3b, v48
	v_exp_f32_e32 v16, v14
	v_mul_f32_e32 v51, v11, v69
	v_pk_mul_f32 v[14:15], v[32:33], v[46:47]
	v_mul_f32_e32 v53, v12, v69
	v_add_f32_e32 v10, 1.0, v16
	v_mul_f32_e32 v17, v14, v15
	v_rcp_f32_e32 v14, v10
	v_mul_f32_e32 v10, 0xbfb8aa3b, v50
	v_exp_f32_e32 v10, v10
	v_mov_b32_e32 v15, v34
	v_pk_mul_f32 v[14:15], v[14:15], v[48:49]
	v_mul_f32_e32 v12, 0xbfb8aa3b, v54
	v_add_f32_e32 v10, 1.0, v10
	v_rcp_f32_e32 v34, v10
	v_mul_f32_e32 v10, 0xbfb8aa3b, v52
	v_mul_f32_e32 v14, v14, v15
	v_exp_f32_e32 v15, v10
	v_pk_mul_f32 v[10:11], v[34:35], v[50:51]
	v_exp_f32_e32 v12, v12
	v_mul_f32_e32 v16, v10, v11
	v_add_f32_e32 v10, 1.0, v15
	v_rcp_f32_e32 v10, v10
	v_mov_b32_e32 v11, v36
	v_mov_b32_e32 v55, v37
	v_mul_f32_e32 v7, v7, v69
	v_pk_mul_f32 v[10:11], v[10:11], v[52:53]
	v_and_b32_e32 v28, 0xffff0000, v28
	v_mul_f32_e32 v15, v10, v11
	v_add_f32_e32 v10, 1.0, v12
	v_rcp_f32_e32 v10, v10
	v_mul_f32_e32 v12, 0xbfb8aa3b, v56
	v_exp_f32_e32 v12, v12
	v_mul_f32_e32 v11, v13, v69
	v_pk_mul_f32 v[10:11], v[10:11], v[54:55]
	v_lshlrev_b32_e32 v66, 16, v29
	v_mul_f32_e32 v32, v10, v11
	v_mul_f32_e32 v11, v6, v69
	v_add_f32_e32 v6, 1.0, v12
	v_rcp_f32_e32 v10, v6
	v_mul_f32_e32 v6, 0xbfb8aa3b, v58
	v_exp_f32_e32 v6, v6
	v_and_b32_e32 v68, 0xffff0000, v29
	v_mul_f32_e32 v3, v3, v69
	v_mul_f32_e32 v5, v5, v69
	v_add_f32_e32 v6, 1.0, v6
	v_rcp_f32_e32 v6, v6
	s_waitcnt vmcnt(0) lgkmcnt(0)
	v_mov_b32_e32 v57, v20
	v_pk_mul_f32 v[10:11], v[10:11], v[56:57]
	v_mov_b32_e32 v59, v21
	v_mul_f32_e32 v20, v10, v11
	v_mul_f32_e32 v10, 0xbfb8aa3b, v60
	v_exp_f32_e32 v10, v10
	v_pk_mul_f32 v[6:7], v[6:7], v[58:59]
	v_mov_b32_e32 v61, v22
	v_mul_f32_e32 v21, v6, v7
	v_add_f32_e32 v6, 1.0, v10
	v_mul_f32_e32 v7, v8, v69
	v_rcp_f32_e32 v6, v6
	v_mul_f32_e32 v8, 0xbfb8aa3b, v62
	v_exp_f32_e32 v8, v8
	v_mov_b32_e32 v63, v23
	v_pk_mul_f32 v[6:7], v[6:7], v[60:61]
	v_mov_b32_e32 v65, v24
	v_mul_f32_e32 v22, v6, v7
	v_add_f32_e32 v6, 1.0, v8
	v_rcp_f32_e32 v6, v6
	v_mul_f32_e32 v8, 0xbfb8aa3b, v64
	v_exp_f32_e32 v8, v8
	v_mul_f32_e32 v7, v9, v69
	v_pk_mul_f32 v[6:7], v[6:7], v[62:63]
	v_mov_b32_e32 v29, v25
	v_mul_f32_e32 v9, v6, v7
	v_mul_f32_e32 v7, v2, v69
	v_add_f32_e32 v2, 1.0, v8
	v_rcp_f32_e32 v6, v2
	v_mul_f32_e32 v2, 0xbfb8aa3b, v28
	v_exp_f32_e32 v2, v2
	v_mov_b32_e32 v67, v26
	v_pk_mul_f32 v[6:7], v[6:7], v[64:65]
	v_add_f32_e32 v2, 1.0, v2
	v_rcp_f32_e32 v2, v2
	v_mul_f32_e32 v8, v6, v7
	v_mul_f32_e32 v6, 0xbfb8aa3b, v66
	v_exp_f32_e32 v6, v6
	v_pk_mul_f32 v[2:3], v[2:3], v[28:29]
	s_nop 0
	v_mul_f32_e32 v23, v2, v3
	v_mul_f32_e32 v3, 0xbfb8aa3b, v68
	v_add_f32_e32 v2, 1.0, v6
	v_exp_f32_e32 v6, v3
	v_rcp_f32_e32 v2, v2
	v_mul_f32_e32 v3, v4, v69
	v_mov_b32_e32 v69, v27
	v_add_f32_e32 v4, 1.0, v6
	v_rcp_f32_e32 v4, v4
	v_pk_mul_f32 v[2:3], v[2:3], v[66:67]
	s_nop 0
	v_mul_f32_e32 v24, v2, v3
	v_pk_mul_f32 v[2:3], v[4:5], v[68:69]
	s_nop 0
	v_mul_f32_e32 v25, v2, v3
	v_lshlrev_b64 v[2:3], 12, v[18:19]
	v_lshl_add_u64 v[2:3], s[98:99], 0, v[2:3]
	v_lshl_add_u64 v[2:3], v[2:3], 0, s[24:25]
	v_lshl_add_u64 v[10:11], v[2:3], 0, v[0:1]
	v_lshl_add_u64 v[12:13], v[10:11], 0, s[0:1]
	v_add_co_u32_e32 v10, vcc, 0x21300000, v10
	v_cvt_pk_bf16_f32 v2, v40, v30
	v_cvt_pk_bf16_f32 v3, v31, v17
	v_cvt_pk_bf16_f32 v4, v14, v16
	v_cvt_pk_bf16_f32 v5, v15, v32
	s_nop 1
	v_addc_co_u32_e32 v11, vcc, 0, v11, vcc
	v_cvt_pk_bf16_f32 v6, v20, v21
	v_cvt_pk_bf16_f32 v7, v22, v9
	v_cvt_pk_bf16_f32 v8, v8, v23
	v_cvt_pk_bf16_f32 v9, v24, v25
	global_store_dwordx4 v[10:11], v[2:5], off offset:2048
	global_store_dwordx4 v[12:13], v[6:9], off offset:16
	s_cbranch_scc1 .LBB0_144

; #define WAITBAR(N) asm volatile("s_waitcnt vmcnt(" #N ") lgkmcnt(0)\n\ts_barrier" ::: "memory")
; __device__ __forceinline__ void attn_unit(int b, int h, int qb, const bf16_t* __restrict__ proj, const float* __restrict__ btab, float lam, float outscale,
;                                           const float* __restrict__ gain, float* o1scr, bf16_t* merged, LAS char* lds) {
;     ...
;     for (int s = 0; s < 2; ++s) {
;         const int hq = 2 * h + s;
;         const bf16_t* Kh = proj + rowbase * LD + OKK + hq * 64;
;         const bf16_t* Qw = proj + (rowbase + qw + r32) * LD + OQ + hq * 64 + hi * 8;
;         float m_reg = -1e30f, l_reg = 0; f32x16 o[4]; bf16x8 qr[4];
; #pragma unroll
;         for (int d0 = 0; d0 < 4; ++d0) { o[d0] = f32x16{}; qr[d0] = *(const bf16x8*)(Qw + d0 * 16); }
;     ...
;         f32x16 pA0, pA1, pB0, pB1; float mnA, mnB, alA, alB, bo; bf16x8 pa0, pa1, pa2, pa3; constexpr int NT = T / 64;
;         asm volatile("s_waitcnt vmcnt(0) lgkmcnt(0)" ::: "memory"); __syncthreads();
;         DMA_TILE(0, 0); DMA_TILE(1, 1);
;         WAITBAR(3);
.LBB0_187:
	s_or_b32 s24, s6, s48
	s_lshl_b64 s[2:3], s[24:25], 1
	v_lshl_add_u64 v[2:3], v[190:191], 0, s[2:3]
	s_add_u32 s2, s36, s2
	s_addc_u32 s3, s37, s3
	global_load_dwordx4 v[142:145], v[2:3], off
	global_load_dwordx4 v[138:141], v[2:3], off offset:32
	global_load_dwordx4 v[134:137], v[2:3], off offset:64
	global_load_dwordx4 v[130:133], v[2:3], off offset:96
	v_lshl_add_u64 v[184:185], s[2:3], 0, v[186:187]
	s_xor_b64 s[2:3], s[0:1], -1
	s_mov_b64 s[6:7], 0x800
	v_lshl_add_u64 v[184:185], v[184:185], 0, s[6:7]
	v_mov_b64_e32 v[250:251], v[192:193]
	v_mov_b64_e32 v[246:247], v[194:195]
	s_mov_b32 s6, 0xc8000
	s_mov_b32 s7, 0
	v_readfirstlane_b32 s67, v222
	v_add_u32_e32 v239, v226, v227
	v_add_u32_e32 v240, v226, v228
	v_add_u32_e32 v241, v226, v229
	v_add_u32_e32 v242, v226, v230
	s_lshr_b32 s67, s67, 8
	v_add_u32_e32 v239, 0x14000, v239
	v_add_u32_e32 v240, 0x14000, v240
	v_add_u32_e32 v241, 0x14000, v241
	v_add_u32_e32 v242, 0x14000, v242
	v_mov_b32_e32 v243, v215
	v_bfe_u32 v244, v222, 4, 1
	v_bfe_u32 v249, v222, 6, 1
	v_sub_u32_e32 v244, v249, v244
	v_mul_i32_i24_e32 v244, 0xc800, v244
	v_ashrrev_i32_e32 v245, 31, v244
	v_lshl_add_u64 v[250:251], v[250:251], 0, v[244:245]
	v_lshl_add_u64 v[246:247], v[246:247], 0, v[244:245]
	v_mov_b32_e32 v2, 0
	v_mov_b32_e32 v3, 0
	v_mov_b32_e32 v4, 0
	v_mov_b32_e32 v5, 0
	v_mov_b32_e32 v6, 0
	v_mov_b32_e32 v7, 0
	v_mov_b32_e32 v8, 0
	v_mov_b32_e32 v9, 0
	v_mov_b32_e32 v10, 0
	v_mov_b32_e32 v11, 0
	v_mov_b32_e32 v12, 0
	v_mov_b32_e32 v13, 0
	v_mov_b32_e32 v14, 0
	v_mov_b32_e32 v15, 0
	v_mov_b32_e32 v16, 0
	v_mov_b32_e32 v17, 0
	v_mov_b32_e32 v18, 0
	v_mov_b32_e32 v19, 0
	v_mov_b32_e32 v20, 0
	v_mov_b32_e32 v21, 0
	v_mov_b32_e32 v22, 0
	v_mov_b32_e32 v23, 0
	v_mov_b32_e32 v24, 0
	v_mov_b32_e32 v25, 0
	v_mov_b32_e32 v26, 0
	v_mov_b32_e32 v27, 0
	v_mov_b32_e32 v28, 0
	v_mov_b32_e32 v29, 0
	v_mov_b32_e32 v30, 0
	v_mov_b32_e32 v31, 0
	v_mov_b32_e32 v32, 0
	v_mov_b32_e32 v33, 0
	v_mov_b32_e32 v34, 0
	v_mov_b32_e32 v35, 0
	v_mov_b32_e32 v36, 0
	v_mov_b32_e32 v37, 0
	v_mov_b32_e32 v38, 0
	v_mov_b32_e32 v39, 0
	v_mov_b32_e32 v40, 0
	v_mov_b32_e32 v41, 0
	v_mov_b32_e32 v42, 0
	v_mov_b32_e32 v43, 0
	v_mov_b32_e32 v44, 0
	v_mov_b32_e32 v45, 0
	v_mov_b32_e32 v46, 0
	v_mov_b32_e32 v47, 0
	v_mov_b32_e32 v48, 0
	v_mov_b32_e32 v49, 0
	v_mov_b32_e32 v50, 0
	v_mov_b32_e32 v51, 0
	v_mov_b32_e32 v52, 0
	v_mov_b32_e32 v53, 0
	v_mov_b32_e32 v54, 0
	v_mov_b32_e32 v55, 0
	v_mov_b32_e32 v56, 0
	v_mov_b32_e32 v57, 0
	v_mov_b32_e32 v58, 0
	v_mov_b32_e32 v59, 0
	v_mov_b32_e32 v60, 0
	v_mov_b32_e32 v61, 0
	v_mov_b32_e32 v62, 0
	v_mov_b32_e32 v63, 0
	v_mov_b32_e32 v64, 0
	v_mov_b32_e32 v65, 0
	v_mov_b32_e32 v238, 0
	v_add_u32_e32 v245, 0xffffff00, v235
	s_sub_i32 s65, s78, 0x80
	s_mov_b32 s40, 0
	s_waitcnt lgkmcnt(0)
	s_barrier
	s_mov_b32 s24, 0
	s_lshl_b32 s12, s24, 13
	s_add_i32 s12, s12, s66
	s_lshl_b32 s13, s24, 14
	s_add_i32 s13, s13, s74
	s_add_i32 m0, s12, 0x14000
	s_nop 0
	global_load_lds_dwordx4 v[184:185], off
	s_mov_b32 m0, s13
	v_lshl_add_u64 v[184:185], v[184:185], 0, s[6:7]
	global_load_lds_dwordx4 v[250:251], off
	s_add_i32 m0, s13, 0x400
	v_lshl_add_u64 v[250:251], v[250:251], 0, s[6:7]
	global_load_lds_dwordx4 v[246:247], off
	v_lshl_add_u64 v[246:247], v[246:247], 0, s[6:7]
	s_mov_b32 s24, 1
	s_lshl_b32 s12, s24, 13
	s_add_i32 s12, s12, s66
	s_lshl_b32 s13, s24, 14
	s_add_i32 s13, s13, s74
	s_add_i32 m0, s12, 0x14000
	s_nop 0
	global_load_lds_dwordx4 v[184:185], off
	s_mov_b32 m0, s13
	v_lshl_add_u64 v[184:185], v[184:185], 0, s[6:7]
	global_load_lds_dwordx4 v[250:251], off
	s_add_i32 m0, s13, 0x400
	v_lshl_add_u64 v[250:251], v[250:251], 0, s[6:7]
	global_load_lds_dwordx4 v[246:247], off
	v_lshl_add_u64 v[246:247], v[246:247], 0, s[6:7]
	s_waitcnt vmcnt(3)
	s_barrier
	s_cmp_eq_u32 s67, 0
	s_cbranch_scc1 .Lat_enter
	s_barrier
